# v24: v22 + GLA chunk loop MFMA chains (score tiles, output chain) read their LDS operands several MFMAs ahead into spare registers with counted lgkmcnt waits
# speedup vs baseline: 1.0007x; 1.0001x over previous
; #define LAS __attribute__((address_space(3)))
; __device__ __forceinline__ unsigned pk2(float lo, float hi) { f32x2 v = {lo, hi}; bf16x2_t b = __builtin_convertvector(v, bf16x2_t); return __builtin_bit_cast(unsigned, b); }
; __device__ __forceinline__ float bf_lo(unsigned u) { return __uint_as_float(u << 16); }
; __device__ __forceinline__ float bf_hi(unsigned u) { return __uint_as_float(u & 0xffff0000u); }
; __device__ __forceinline__ void gla_item(LAS unsigned char* lds, const bf16_t* __restrict__ GQ, const bf16_t* __restrict__ GK, const float* __restrict__ LA, ...
;     ...
;             f32x2 prefix = {0.f, 0.f}, total = {0.f, 0.f};
; #pragma unroll 4
;             for (int s = 0; s < 16; ++s) { const f32x2 v = segc[s * 32 + dp]; total += v; if (s < sg) prefix += v; }
;             f32x2 etot; etot.x = __expf(total.x); etot.y = __expf(total.y);
;             float kd0[4], kd1[4];
; #pragma unroll
;             for (int i = 0; i < 4; ++i) { const f32x2 cm = prefix + cum[i]; f32x2 ep, em; ep.x = __expf(cm.x); ep.y = __expf(cm.y);
;                 em.x = __builtin_amdgcn_rcpf(ep.x); em.y = __builtin_amdgcn_rcpf(ep.y);
;                 const float q0 = bf_lo(q_n[i]), q1 = bf_hi(q_n[i]), k0 = bf_lo(k_n[i]), k1 = bf_hi(k_n[i]);
;                 const int o = (4 * sg + i) * KP + dp * 4;
;                 *(LAS unsigned*)(lds + O_QF + o) = pk2(q0 * ep.x, q1 * ep.y);
;                 *(LAS unsigned*)(lds + O_QB + o) = pk2(q0 * em.x, q1 * em.y);
;                 *(LAS unsigned*)(lds + O_KF + o) = pk2(k0 * em.x, k1 * em.y);
;                 *(LAS unsigned*)(lds + O_KB + o) = pk2(k0 * ep.x, k1 * ep.y);
;                 kd0[i] = k0 * (etot.x * em.x); kd1[i] = k1 * (etot.y * em.y); }
.LBB0_381:
	v_cndmask_b32_e64 v18, 0, 1, s[84:85]
	s_mov_b32 s51, s50
	v_lshl_add_u32 v22, v18, 12, v128
	s_mov_b32 s48, 0
	v_mov_b32_e32 v18, 0
	v_mov_b32_e32 v19, v129
	v_mov_b32_e32 v20, 0
	v_mov_b32_e32 v21, v129
	v_add_u32_e32 v176, 0x800, v22
	ds_read2_b64 v[180:183], v22 offset1:32
	ds_read2_b64 v[184:187], v22 offset0:64 offset1:96
	ds_read2_b64 v[188:191], v22 offset0:128 offset1:160
	ds_read2_b64 v[192:195], v22 offset0:192 offset1:224
	ds_read2_b64 v[196:199], v176 offset1:32
	ds_read2_b64 v[200:203], v176 offset0:64 offset1:96
	ds_read2_b64 v[204:207], v176 offset0:128 offset1:160
	ds_read2_b64 v[208:211], v176 offset0:192 offset1:224
	s_waitcnt lgkmcnt(7)
	v_cmp_lt_i32_e32 vcc, 0, v103
	v_pk_add_f32 v[20:21], v[20:21], v[180:181]
	v_pk_add_f32 v[24:25], v[18:19], v[180:181]
	v_cndmask_b32_e32 v19, v19, v25, vcc
	v_cndmask_b32_e32 v18, v18, v24, vcc
	v_cmp_lt_i32_e32 vcc, 1, v103
	v_pk_add_f32 v[20:21], v[20:21], v[182:183]
	v_pk_add_f32 v[24:25], v[18:19], v[182:183]
	v_cndmask_b32_e32 v19, v19, v25, vcc
	v_cndmask_b32_e32 v18, v18, v24, vcc
	s_waitcnt lgkmcnt(6)
	v_cmp_lt_i32_e32 vcc, 2, v103
	v_pk_add_f32 v[20:21], v[20:21], v[184:185]
	v_pk_add_f32 v[24:25], v[18:19], v[184:185]
	v_cndmask_b32_e32 v19, v19, v25, vcc
	v_cndmask_b32_e32 v18, v18, v24, vcc
	v_cmp_lt_i32_e32 vcc, 3, v103
	v_pk_add_f32 v[20:21], v[20:21], v[186:187]
	v_pk_add_f32 v[24:25], v[18:19], v[186:187]
	v_cndmask_b32_e32 v19, v19, v25, vcc
	v_cndmask_b32_e32 v18, v18, v24, vcc
	s_waitcnt lgkmcnt(5)
	v_cmp_lt_i32_e32 vcc, 4, v103
	v_pk_add_f32 v[20:21], v[20:21], v[188:189]
	v_pk_add_f32 v[24:25], v[18:19], v[188:189]
	v_cndmask_b32_e32 v19, v19, v25, vcc
	v_cndmask_b32_e32 v18, v18, v24, vcc
	v_cmp_lt_i32_e32 vcc, 5, v103
	v_pk_add_f32 v[20:21], v[20:21], v[190:191]
	v_pk_add_f32 v[24:25], v[18:19], v[190:191]
	v_cndmask_b32_e32 v19, v19, v25, vcc
	v_cndmask_b32_e32 v18, v18, v24, vcc
	s_waitcnt lgkmcnt(4)
	v_cmp_lt_i32_e32 vcc, 6, v103
	v_pk_add_f32 v[20:21], v[20:21], v[192:193]
	v_pk_add_f32 v[24:25], v[18:19], v[192:193]
	v_cndmask_b32_e32 v19, v19, v25, vcc
	v_cndmask_b32_e32 v18, v18, v24, vcc
	v_cmp_lt_i32_e32 vcc, 7, v103
	v_pk_add_f32 v[20:21], v[20:21], v[194:195]
	v_pk_add_f32 v[24:25], v[18:19], v[194:195]
	v_cndmask_b32_e32 v19, v19, v25, vcc
	v_cndmask_b32_e32 v18, v18, v24, vcc
	s_waitcnt lgkmcnt(3)
	v_cmp_lt_i32_e32 vcc, 8, v103
	v_pk_add_f32 v[20:21], v[20:21], v[196:197]
	v_pk_add_f32 v[24:25], v[18:19], v[196:197]
	v_cndmask_b32_e32 v19, v19, v25, vcc
	v_cndmask_b32_e32 v18, v18, v24, vcc
	v_cmp_lt_i32_e32 vcc, 9, v103
	v_pk_add_f32 v[20:21], v[20:21], v[198:199]
	v_pk_add_f32 v[24:25], v[18:19], v[198:199]
	v_cndmask_b32_e32 v19, v19, v25, vcc
	v_cndmask_b32_e32 v18, v18, v24, vcc
	s_waitcnt lgkmcnt(2)
	v_cmp_lt_i32_e32 vcc, 10, v103
	v_pk_add_f32 v[20:21], v[20:21], v[200:201]
	v_pk_add_f32 v[24:25], v[18:19], v[200:201]
	v_cndmask_b32_e32 v19, v19, v25, vcc
	v_cndmask_b32_e32 v18, v18, v24, vcc
	v_cmp_lt_i32_e32 vcc, 11, v103
	v_pk_add_f32 v[20:21], v[20:21], v[202:203]
	v_pk_add_f32 v[24:25], v[18:19], v[202:203]
	v_cndmask_b32_e32 v19, v19, v25, vcc
	v_cndmask_b32_e32 v18, v18, v24, vcc
	s_waitcnt lgkmcnt(1)
	v_cmp_lt_i32_e32 vcc, 12, v103
	v_pk_add_f32 v[20:21], v[20:21], v[204:205]
	v_pk_add_f32 v[24:25], v[18:19], v[204:205]
	v_cndmask_b32_e32 v19, v19, v25, vcc
	v_cndmask_b32_e32 v18, v18, v24, vcc
	v_cmp_lt_i32_e32 vcc, 13, v103
	v_pk_add_f32 v[20:21], v[20:21], v[206:207]
	v_pk_add_f32 v[24:25], v[18:19], v[206:207]
	v_cndmask_b32_e32 v19, v19, v25, vcc
	v_cndmask_b32_e32 v18, v18, v24, vcc
	s_waitcnt lgkmcnt(0)
	v_cmp_lt_i32_e32 vcc, 14, v103
	v_pk_add_f32 v[20:21], v[20:21], v[208:209]
	v_pk_add_f32 v[24:25], v[18:19], v[208:209]
	v_cndmask_b32_e32 v19, v19, v25, vcc
	v_cndmask_b32_e32 v18, v18, v24, vcc
	v_cmp_lt_i32_e32 vcc, 15, v103
	v_pk_add_f32 v[20:21], v[20:21], v[210:211]
	v_pk_add_f32 v[24:25], v[18:19], v[210:211]
	v_cndmask_b32_e32 v19, v19, v25, vcc
	v_cndmask_b32_e32 v18, v18, v24, vcc
	v_pk_add_f32 v[16:17], v[16:17], v[18:19]
	s_waitcnt vmcnt(19)
	v_lshlrev_b32_e32 v28, 16, v120
	v_mul_f32_e32 v16, 0x3fb8aa3b, v16
	v_exp_f32_e32 v22, v16
	v_mul_f32_e32 v16, 0x3fb8aa3b, v17
	v_exp_f32_e32 v23, v16
	v_and_b32_e32 v29, 0xffff0000, v120
	v_rcp_f32_e32 v24, v22
	s_waitcnt vmcnt(18)
	v_lshlrev_b32_e32 v26, 16, v121
	v_rcp_f32_e32 v25, v23
	v_and_b32_e32 v27, 0xffff0000, v121
	v_pk_mul_f32 v[30:31], v[22:23], v[28:29]
	v_mul_f32_e32 v16, 0x3fb8aa3b, v21
	v_pk_mul_f32 v[28:29], v[24:25], v[28:29]
	v_pk_mul_f32 v[22:23], v[22:23], v[26:27]
	v_cvt_pk_bf16_f32 v21, v28, v29
	v_pk_mul_f32 v[28:29], v[24:25], v[26:27]
	v_cvt_pk_bf16_f32 v37, v22, v23
	v_cvt_pk_bf16_f32 v36, v28, v29
	v_pk_add_f32 v[28:29], v[44:45], v[18:19]
	s_waitcnt vmcnt(17)
	v_lshlrev_b32_e32 v32, 16, v118
	v_mul_f32_e32 v28, 0x3fb8aa3b, v28
	v_mul_f32_e32 v29, 0x3fb8aa3b, v29
	v_exp_f32_e32 v28, v28
	v_exp_f32_e32 v29, v29
	v_and_b32_e32 v33, 0xffff0000, v118
	v_exp_f32_e32 v16, v16
	v_rcp_f32_e32 v22, v28
	v_rcp_f32_e32 v23, v29
	v_pk_mul_f32 v[34:35], v[28:29], v[32:33]
	v_cvt_pk_bf16_f32 v17, v30, v31
	s_waitcnt vmcnt(16)
; __device__ __forceinline__ void gla_item(LAS unsigned char* lds, const bf16_t* __restrict__ GQ, const bf16_t* __restrict__ GK, const float* __restrict__ LA, ...
;     ...
;             for (int i = 0; i < 4; ++i) { const f32x2 cm = prefix + cum[i]; f32x2 ep, em; ep.x = __expf(cm.x); ep.y = __expf(cm.y);
;                 em.x = __builtin_amdgcn_rcpf(ep.x); em.y = __builtin_amdgcn_rcpf(ep.y);
;                 const float q0 = bf_lo(q_n[i]), q1 = bf_hi(q_n[i]), k0 = bf_lo(k_n[i]), k1 = bf_hi(k_n[i]);
;                 const int o = (4 * sg + i) * KP + dp * 4;
;                 *(LAS unsigned*)(lds + O_QF + o) = pk2(q0 * ep.x, q1 * ep.y);
;                 *(LAS unsigned*)(lds + O_QB + o) = pk2(q0 * em.x, q1 * em.y);
;                 *(LAS unsigned*)(lds + O_KF + o) = pk2(k0 * em.x, k1 * em.y);
;                 *(LAS unsigned*)(lds + O_KB + o) = pk2(k0 * ep.x, k1 * ep.y);
;                 kd0[i] = k0 * (etot.x * em.x); kd1[i] = k1 * (etot.y * em.y); }
;             u32x2 w0, w1; w0.x = pk2(kd0[0], kd0[1]); w0.y = pk2(kd0[2], kd0[3]); w1.x = pk2(kd1[0], kd1[1]); w1.y = pk2(kd1[2], kd1[3]);
;             *(LAS u32x2*)(lds + O_KDT + (2 * dp) * KP + sg * 8) = w0;
;             *(LAS u32x2*)(lds + O_KDT + (2 * dp + 1) * KP + sg * 8) = w1;
;             if (sg == 0) { dec[2 * dp] = etot.x; dec[2 * dp + 1] = etot.y; }
; #pragma unroll
;             for (int j = 0; j < 2; ++j) { const int c = tid + 512 * j; const int ch = c & 7; LAS unsigned char* vp = lds + O_VT + (c >> 3) * KP + ((ch >> 1) * 16 + (ch & 1) * 4) * 2;
;                 u32x2 lo, hi; lo.x = v_n[j].x; lo.y = v_n[j].y; hi.x = v_n[j].z; hi.y = v_n[j].w; *(LAS u32x2*)vp = lo; *(LAS u32x2*)(vp + 16) = hi; }
;             { const int n1 = (n + 1 < SEQ / 64) ? n + 1 : n;
; #pragma unroll
;               for (int i = 0; i < 4; ++i) { const size_t o1 = rbase + (size_t)n1 * 64 * 256 + i * 256; q_n[i] = *(const unsigned*)(GQ + o1); k_n[i] = *(const unsigned*)(GK + o1); }
; #pragma unroll
;               for (int j = 0; j < 2; ++j) v_n[j] = *(const u32x4*)(vbase0 + (size_t)j * 64 * SEQ + 64 * n1); }
;         }
;         __syncthreads();
;         if (wid < 4) {
;             const int ltile = (wid == 1 || wid == 2) ? 1 : 0, mtile = (wid == 1 || wid == 3) ? 1 : 0;
;             const bool needf = (wid != 3), needb = (wid != 2);
;             f32x16 af, ab;
; #pragma unroll
	v_lshlrev_b32_e32 v30, 16, v119
	v_and_b32_e32 v31, 0xffff0000, v119
	v_cvt_pk_bf16_f32 v34, v34, v35
	v_pk_mul_f32 v[32:33], v[22:23], v[32:33]
	ds_write2_b32 v130, v17, v34 offset1:36
	v_cvt_pk_bf16_f32 v17, v32, v33
	v_add_u32_e32 v38, 0x2400, v130
	v_pk_mul_f32 v[32:33], v[22:23], v[30:31]
	ds_write2_b32 v38, v21, v17 offset1:36
	v_cvt_pk_bf16_f32 v17, v32, v33
	v_add_u32_e32 v21, 0x4800, v130
	v_pk_mul_f32 v[28:29], v[28:29], v[30:31]
	ds_write2_b32 v21, v36, v17 offset1:36
	v_cvt_pk_bf16_f32 v17, v28, v29
	v_add_u32_e32 v39, 0x6c00, v130
	v_mov_b32_e32 v28, v24
	v_mov_b32_e32 v29, v22
	v_mov_b32_e32 v22, v25
	v_pk_add_f32 v[24:25], v[42:43], v[18:19]
	v_mul_f32_e32 v20, 0x3fb8aa3b, v20
	ds_write2_b32 v39, v37, v17 offset1:36
	v_pk_mul_f32 v[22:23], v[16:17], v[22:23] op_sel_hi:[0,1]
	v_mul_f32_e32 v17, 0x3fb8aa3b, v24
	v_exp_f32_e32 v20, v20
	v_exp_f32_e32 v24, v17
	v_mul_f32_e32 v17, 0x3fb8aa3b, v25
	v_exp_f32_e32 v25, v17
	v_pk_add_f32 v[18:19], v[40:41], v[18:19]
	v_pk_mul_f32 v[28:29], v[20:21], v[28:29] op_sel_hi:[0,1]
	v_mul_f32_e32 v18, 0x3fb8aa3b, v18
	v_mul_f32_e32 v19, 0x3fb8aa3b, v19
	v_exp_f32_e32 v18, v18
	v_exp_f32_e32 v19, v19
	v_mov_b32_e32 v32, v26
	v_mov_b32_e32 v33, v30
	v_mov_b32_e32 v30, v27
	v_pk_mul_f32 v[28:29], v[28:29], v[32:33]
	v_pk_mul_f32 v[22:23], v[22:23], v[30:31]
	v_rcp_f32_e32 v26, v24
	v_rcp_f32_e32 v27, v25
	s_waitcnt vmcnt(14)
	v_lshlrev_b32_e32 v30, 16, v115
	v_and_b32_e32 v31, 0xffff0000, v115
	v_lshlrev_b32_e32 v32, 16, v113
	v_and_b32_e32 v33, 0xffff0000, v113
	v_pk_mul_f32 v[34:35], v[24:25], v[32:33]
	v_pk_mul_f32 v[24:25], v[24:25], v[30:31]
	v_cvt_pk_bf16_f32 v17, v34, v35
	v_cvt_pk_bf16_f32 v40, v24, v25
	v_rcp_f32_e32 v24, v18
	v_rcp_f32_e32 v25, v19
	v_pk_mul_f32 v[32:33], v[26:27], v[32:33]
	s_waitcnt vmcnt(12)
	v_lshlrev_b32_e32 v34, 16, v112
	v_and_b32_e32 v35, 0xffff0000, v112
	v_cvt_pk_bf16_f32 v42, v32, v33
	v_pk_mul_f32 v[32:33], v[26:27], v[30:31]
	v_pk_mul_f32 v[36:37], v[18:19], v[34:35]
	v_cvt_pk_bf16_f32 v43, v32, v33
	v_lshlrev_b32_e32 v32, 16, v114
	v_and_b32_e32 v33, 0xffff0000, v114
	v_cvt_pk_bf16_f32 v36, v36, v37
	v_pk_mul_f32 v[34:35], v[24:25], v[34:35]
	ds_write2_b32 v130, v17, v36 offset0:72 offset1:108
	v_cvt_pk_bf16_f32 v17, v34, v35
	v_pk_mul_f32 v[34:35], v[24:25], v[32:33]
	ds_write2_b32 v38, v42, v17 offset0:72 offset1:108
	v_cvt_pk_bf16_f32 v17, v34, v35
	v_pk_mul_f32 v[18:19], v[18:19], v[32:33]
	ds_write2_b32 v21, v43, v17 offset0:72 offset1:108
	v_cvt_pk_bf16_f32 v17, v18, v19
	v_mov_b32_e32 v18, v26
	v_mov_b32_e32 v19, v24
	v_pk_mul_f32 v[18:19], v[20:21], v[18:19] op_sel_hi:[0,1]
	v_mov_b32_e32 v34, v30
	v_mov_b32_e32 v35, v32
	v_mov_b32_e32 v24, v27
	v_pk_mul_f32 v[18:19], v[18:19], v[34:35]
	v_pk_mul_f32 v[24:25], v[16:17], v[24:25] op_sel_hi:[0,1]
	v_mov_b32_e32 v32, v31
	v_pk_mul_f32 v[24:25], v[24:25], v[32:33]
	v_cvt_pk_bf16_f32 v26, v28, v29
	v_cvt_pk_bf16_f32 v27, v18, v19
	ds_write2_b32 v39, v40, v17 offset0:72 offset1:108
	v_cvt_pk_bf16_f32 v18, v22, v23
	v_cvt_pk_bf16_f32 v19, v24, v25
	ds_write_b64 v131, v[26:27] offset:36864
	ds_write_b64 v132, v[18:19] offset:36864
	s_and_saveexec_b64 s[86:87], s[0:1]
	v_mov_b32_e32 v21, v16
	ds_write_b64 v110, v[20:21]
	s_or_b64 exec, exec, s[86:87]
	s_add_i32 s50, s51, 1
	s_cmp_lg_u32 s51, 63
	s_cselect_b32 s56, s50, 63
	s_lshl_b32 s48, s56, 14
	v_lshl_add_u64 v[16:17], v[80:81], 0, s[48:49]
	s_lshl_b32 s48, s56, 15
	s_waitcnt vmcnt(7)
	ds_write2_b64 v136, v[56:57], v[58:59] offset0:128 offset1:130
	s_waitcnt vmcnt(5)
	ds_write2_b64 v137, v[60:61], v[62:63] offset0:128 offset1:130
	v_lshl_add_u64 v[18:19], v[88:89], 0, s[48:49]
	v_lshl_add_u64 v[20:21], v[90:91], 0, s[48:49]
	v_lshlrev_b64 v[16:17], 1, v[16:17]
	s_mov_b64 s[58:59], 0x400
	global_load_dword v120, v[18:19], off
	global_load_dword v121, v[20:21], off
	global_load_dword v118, v[18:19], off offset:512
	global_load_dword v119, v[20:21], off offset:512
	v_lshl_add_u64 v[18:19], v[16:17], 0, s[58:59]
	s_mov_b64 s[58:59], 0x600
	v_lshl_add_u64 v[20:21], s[66:67], 0, v[18:19]
	v_lshl_add_u64 v[18:19], s[68:69], 0, v[18:19]
	v_lshl_add_u64 v[16:17], v[16:17], 0, s[58:59]
	global_load_dword v115, v[18:19], off
	v_lshl_add_u64 v[18:19], s[66:67], 0, v[16:17]
	v_lshl_add_u64 v[16:17], s[68:69], 0, v[16:17]
	s_lshl_b32 s48, s56, 7
	global_load_dword v112, v[18:19], off
	global_load_dword v114, v[16:17], off
	v_lshl_add_u64 v[16:17], v[86:87], 0, s[48:49]
	global_load_dword v113, v[20:21], off
	global_load_dwordx4 v[56:59], v[16:17], off
	v_add_co_u32_e32 v16, vcc, 0x80000, v16
	s_nop 1
	v_addc_co_u32_e32 v17, vcc, 0, v17, vcc
	global_load_dwordx4 v[60:63], v[16:17], off
	s_andn2_b64 vcc, exec, s[78:79]
	s_waitcnt lgkmcnt(0)
	s_barrier
	s_cbranch_vccnz .LBB0_391
	v_mov_b32_e32 v16, 0
	s_andn2_b64 vcc, exec, s[80:81]
	v_mov_b32_e32 v32, 0
	v_mov_b32_e32 v33, 0
	v_mov_b32_e32 v34, 0
	v_mov_b32_e32 v35, 0
	v_mov_b32_e32 v36, 0
	v_mov_b32_e32 v37, 0
	v_mov_b32_e32 v38, 0
	v_mov_b32_e32 v39, 0
	v_mov_b32_e32 v40, 0
	v_mov_b32_e32 v41, 0
	v_mov_b32_e32 v42, 0
	v_mov_b32_e32 v43, 0
	v_mov_b32_e32 v44, 0
	v_mov_b32_e32 v45, 0
	v_mov_b32_e32 v46, 0
	v_mov_b32_e32 v47, 0
	s_cbranch_vccnz .LBB0_388
	ds_read_b128 v[18:21], v138 offset:18432
	ds_read_b128 v[22:25], v139
	ds_read_b128 v[212:215], v138 offset:18464
	ds_read_b128 v[216:219], v139 offset:32
	ds_read_b128 v[220:223], v138 offset:18496
	ds_read_b128 v[224:227], v139 offset:64
	ds_read_b128 v[228:231], v138 offset:18528
	ds_read_b128 v[232:235], v139 offset:96
	s_waitcnt lgkmcnt(6)
	v_mfma_f32_32x32x16_bf16 v[32:47], v[18:21], v[22:25], 0
	s_waitcnt lgkmcnt(4)
	v_mfma_f32_32x32x16_bf16 v[32:47], v[212:215], v[216:219], v[32:47]
	s_waitcnt lgkmcnt(2)
	v_mfma_f32_32x32x16_bf16 v[32:47], v[220:223], v[224:227], v[32:47]
	s_waitcnt lgkmcnt(0)
	v_mfma_f32_32x32x16_bf16 v[32:47], v[228:231], v[232:235], v[32:47]
.LBB0_388:
	s_andn2_b64 vcc, exec, s[82:83]
	v_mov_b32_e32 v17, 0
	v_mov_b32_e32 v18, 0
	v_mov_b32_e32 v19, 0
	v_mov_b32_e32 v20, 0
	v_mov_b32_e32 v21, 0
	v_mov_b32_e32 v22, 0
	v_mov_b32_e32 v23, 0
	v_mov_b32_e32 v24, 0
	v_mov_b32_e32 v25, 0
	v_mov_b32_e32 v26, 0
	v_mov_b32_e32 v27, 0
	v_mov_b32_e32 v28, 0
	v_mov_b32_e32 v29, 0
	v_mov_b32_e32 v30, 0
	v_mov_b32_e32 v31, 0
	s_cbranch_vccnz .LBB0_390
	ds_read_b128 v[16:19], v138 offset:27648
	ds_read_b128 v[20:23], v139 offset:9216
	ds_read_b128 v[140:143], v138 offset:27680
	ds_read_b128 v[148:151], v139 offset:9248
	ds_read_b128 v[212:215], v138 offset:27712
	ds_read_b128 v[216:219], v139 offset:9280
	ds_read_b128 v[220:223], v138 offset:27744
	ds_read_b128 v[224:227], v139 offset:9312
	s_waitcnt lgkmcnt(6)
	v_mfma_f32_32x32x16_bf16 v[16:31], v[16:19], v[20:23], 0
	s_waitcnt lgkmcnt(4)
	v_mfma_f32_32x32x16_bf16 v[16:31], v[140:143], v[148:151], v[16:31]
	s_waitcnt lgkmcnt(2)
	v_mfma_f32_32x32x16_bf16 v[16:31], v[212:215], v[216:219], v[16:31]
	s_waitcnt lgkmcnt(0)
	v_mfma_f32_32x32x16_bf16 v[16:31], v[220:223], v[224:227], v[16:31]

; #define LAS __attribute__((address_space(3)))
; __device__ __forceinline__ void gla_item(LAS unsigned char* lds, const bf16_t* __restrict__ GQ, const bf16_t* __restrict__ GK, const float* __restrict__ LA, ...
;     ...
;         for (int i = 0; i < 4; ++i) cum[i] = la_n[i];
; #pragma unroll
;         for (int i = 1; i < 4; ++i) cum[i] += cum[i - 1];
;         segn[sg * 32 + dp] = cum[3];
;         { const int n2 = (n + 2 < SEQ / 64) ? n + 2 : SEQ / 64 - 1;
; #pragma unroll
;           for (int i = 0; i < 4; ++i) la_n[i] = *(const f32x2*)(LA + rbase + (size_t)n2 * 64 * 256 + i * 256); }
;         __syncthreads();
;         f32x16 o;
; #pragma unroll
;         for (int i = 0; i < 16; ++i) o[i] = 0.f;
;         {
;             const int vo = (32 * dvt + r) * KP + hh * 16, lo = (32 * lt + r) * KP + hh * 16;
; #pragma unroll
;             for (int s = 0; s < 4; ++s) o = __builtin_amdgcn_mfma_f32_32x32x16_bf16(*(const LAS bf16x8*)(lds + O_VT + vo + s * 32), *(const LAS bf16x8*)(lds + O_AL + lo + s * 32), o, 0, 0, 0);
; #pragma unroll
;             for (int s = 0; s < 4; ++s) o = __builtin_amdgcn_mfma_f32_32x32x16_bf16(*(const LAS bf16x8*)(lds + O_ST + vo + s * 32), *(const LAS bf16x8*)(lds + O_QF + lo + s * 32), o, 0, 0, 0);
; #pragma unroll
;             for (int g4 = 0; g4 < 4; ++g4) { const f32x4 dc = *(const LAS f32x4*)(dec + 32 * dkt + 8 * g4 + 4 * hh);
; #pragma unroll
;                 for (int j = 0; j < 4; ++j) S[4 * g4 + j] *= dc[j]; }
;             const int ka = (32 * dkt + r) * KP + hh * 16;
; #pragma unroll
;             for (int s = 0; s < 4; ++s) S = __builtin_amdgcn_mfma_f32_32x32x16_bf16(*(const LAS bf16x8*)(lds + O_KDT + ka + s * 32), *(const LAS bf16x8*)(lds + O_VT + vo + s * 32), S, 0, 0, 0);
;         }
;         float ss = 0.f;
; #pragma unroll
;         for (int i = 0; i < 16; ++i) ss += o[i] * o[i];
;         ss += __shfl_xor(ss, 32);
;         if (hh == 0) ssq[(lt * 4 + dvt) * 32 + r] = ss;
.LBB0_393:
	s_lshl_b32 s48, s50, 12
	s_waitcnt vmcnt(14)
	v_pk_add_f32 v[44:45], v[98:99], v[94:95]
	s_and_b32 s48, s48, 0x1000
	s_waitcnt vmcnt(13)
	v_pk_add_f32 v[42:43], v[96:97], v[44:45]
	v_add_u32_e32 v16, s48, v106
	s_min_u32 s48, s51, 61
	s_waitcnt vmcnt(12)
	v_pk_add_f32 v[40:41], v[100:101], v[42:43]
	s_lshl_b32 s48, s48, 16
	ds_write_b64 v16, v[40:41]
	v_lshl_add_u64 v[16:17], v[82:83], 0, s[48:49]
	v_add_co_u32_e32 v16, vcc, 0x20000, v16
	v_add_u32_e32 v146, 0x14400, v135
	s_nop 0
	v_addc_co_u32_e32 v17, vcc, 0, v17, vcc
	global_load_dwordx2 v[46:47], v[16:17], off
	global_load_dwordx2 v[98:99], v[16:17], off offset:1024
	global_load_dwordx2 v[96:97], v[16:17], off offset:2048
	global_load_dwordx2 v[100:101], v[16:17], off offset:3072
	s_waitcnt lgkmcnt(0)
	s_barrier
	ds_read_b128 v[140:143], v134 offset:46080
	ds_read_b128 v[16:19], v146
	ds_read_b128 v[148:151], v134 offset:46112
	ds_read_b128 v[32:35], v146 offset:32
	ds_read_b128 v[212:215], v134 offset:46144
	ds_read_b128 v[36:39], v146 offset:64
	ds_read_b128 v[216:219], v134 offset:46176
	ds_read_b128 v[152:155], v146 offset:96
	ds_read_b128 v[220:223], v134 offset:64512
	ds_read_b128 v[162:165], v135
	ds_read_b128 v[224:227], v134 offset:64544
	ds_read_b128 v[166:169], v135 offset:32
	ds_read_b128 v[228:231], v134 offset:64576
	ds_read_b128 v[232:235], v135 offset:64
	v_add_u32_e32 v146, s45, v102
	s_waitcnt lgkmcnt(12)
	v_mfma_f32_32x32x16_bf16 v[16:31], v[140:143], v[16:19], 0
	s_waitcnt lgkmcnt(10)
	v_mfma_f32_32x32x16_bf16 v[16:31], v[148:151], v[32:35], v[16:31]
	ds_read_b128 v[32:35], v134 offset:64608
	s_waitcnt lgkmcnt(9)
	v_mfma_f32_32x32x16_bf16 v[16:31], v[212:215], v[36:39], v[16:31]
	ds_read_b128 v[36:39], v135 offset:96
	s_waitcnt lgkmcnt(8)
	v_mfma_f32_32x32x16_bf16 v[16:31], v[216:219], v[152:155], v[16:31]
	ds_read_b128 v[152:155], v146
	s_waitcnt lgkmcnt(7)
	v_mfma_f32_32x32x16_bf16 v[16:31], v[220:223], v[162:165], v[16:31]
	ds_read_b128 v[162:165], v146 offset:32
	ds_read_b128 v[220:223], v135 offset:36864
	s_waitcnt lgkmcnt(7)
	v_mfma_f32_32x32x16_bf16 v[16:31], v[224:227], v[166:169], v[16:31]
	ds_read_b128 v[166:169], v146 offset:64
	ds_read_b128 v[170:173], v146 offset:96
	ds_read_b128 v[224:227], v135 offset:36896
	s_waitcnt lgkmcnt(8)
	v_mfma_f32_32x32x16_bf16 v[16:31], v[228:231], v[232:235], v[16:31]
	ds_read_b128 v[228:231], v135 offset:36928
	ds_read_b128 v[232:235], v135 offset:36960
	s_waitcnt lgkmcnt(8)
	v_mfma_f32_32x32x16_bf16 v[16:31], v[32:35], v[36:39], v[16:31]
	s_waitcnt lgkmcnt(3)
	v_pk_mul_f32 v[2:3], v[2:3], v[154:155]
	v_pk_mul_f32 v[0:1], v[0:1], v[152:153]
	v_pk_mul_f32 v[12:13], v[12:13], v[170:171]
	v_pk_mul_f32 v[8:9], v[8:9], v[166:167]
	v_pk_mul_f32 v[4:5], v[4:5], v[162:163]
	v_pk_mul_f32 v[14:15], v[14:15], v[172:173]
	v_pk_mul_f32 v[10:11], v[10:11], v[168:169]
	v_pk_mul_f32 v[6:7], v[6:7], v[164:165]
	s_nop 1
	v_mfma_f32_32x32x16_bf16 v[0:15], v[220:223], v[140:143], v[0:15]
	s_waitcnt lgkmcnt(2)
	v_mfma_f32_32x32x16_bf16 v[0:15], v[224:227], v[148:151], v[0:15]
	s_waitcnt lgkmcnt(1)
	v_mfma_f32_32x32x16_bf16 v[0:15], v[228:231], v[212:215], v[0:15]
	s_waitcnt lgkmcnt(0)
	v_mfma_f32_32x32x16_bf16 v[0:15], v[232:235], v[216:219], v[0:15]
	v_mul_f32_e32 v32, v17, v17
	v_fmac_f32_e32 v32, v16, v16
	v_fmac_f32_e32 v32, v18, v18
	v_fmac_f32_e32 v32, v19, v19
	v_fmac_f32_e32 v32, v20, v20
	v_fmac_f32_e32 v32, v21, v21
	v_fmac_f32_e32 v32, v22, v22
	v_fmac_f32_e32 v32, v23, v23
	v_fmac_f32_e32 v32, v24, v24
	v_fmac_f32_e32 v32, v25, v25
	v_fmac_f32_e32 v32, v26, v26
	v_fmac_f32_e32 v32, v27, v27
	v_fmac_f32_e32 v32, v28, v28
	v_fmac_f32_e32 v32, v29, v29
	v_fmac_f32_e32 v32, v30, v30
	v_fmac_f32_e32 v32, v31, v31
	ds_bpermute_b32 v33, v108, v32
	s_and_saveexec_b64 s[86:87], s[4:5]
	s_cbranch_execz .LBB0_380
	s_waitcnt lgkmcnt(0)
	v_add_f32_e32 v32, v32, v33
	ds_write_b32 v116, v32
	s_branch .LBB0_380
